# GEMM2b as 4 sub-passes: 8 special WGs take 4 split tiles + sample tile, other 248 WGs take split rows [0,76) and full-K rows (balanced 210/236/230 loads)
# speedup vs baseline: 1.0057x; 1.0036x over previous
; __global__ void __launch_bounds__(NWAVES * 64, 2) hybrid_fwd(Args A) {
;     ...
;             else if ((s == 2 && EN(3)) || (s == 3 && EN(4)) || (s == 4 && EN(5))) {
;                 const bool split = C.G >= 192; bool go = (s == 4); int k0 = split ? KSPLIT : 0, kl = D - k0, gg = C.G, cc = C.bid, mrows = M; size_t roff = 0;
;                 if (s == 2) { go = phase_mixers(A, C, l, rep ? DUP_UN : 7); k0 = 0; kl = KSPLIT; gg = C.G - 128; cc = C.bid - 128; mrows = MP; }
;                 if (s == 3) { phase_post(A, C, l, split ? 8 : 0); go = split && C.bid < 8 && !rep; k0 = 0; kl = KSPLIT; gg = 8; cc = C.bid; mrows = MS; roff = (size_t)MP * D; }
;                 if (go) { pg8::Gemm g{WS_PTR(const bf16, WS_XN) + roff + k0, WS_PTR(const bf16, WS_WOUTT) + (size_t)l * D * D + k0, mrows, D, kl, D}; pg8::StaticOrder S; S.init(mrows, D, gg, cc);
;                     const bool first = (l == 0) && (s != 4 || !split);
;                     float* Hout = ((rep && s == 4) ? WS_PTR(float, WS_U) : A.out) + roff;
;                     pg8::EpiResN E{Hout, first ? (s == 3 ? A.in[I_XS] : A.in[I_XP]) : Hout, first ? A.in[I_XS] - (size_t)MP * D : Hout, WS_PTR(bf16, WS_HB), WS_PTR(float, WS_SS) + (size_t)(l + 1) * M, s == 4 && !rep};
;                     pg8::gemm_phase<pg8::EpiResN, pg8::StaticOrder, G2_ALIGN, true>(C.lds, g, S, E); }
.Lmy_g2_next:
	v_readlane_b32 s0, v255, 61
	s_add_i32 s0, s0, 1
	v_writelane_b32 v255, s0, 61
	v_readlane_b32 s1, v253, 0
	s_cmp_eq_u32 s0, 0
	s_cbranch_scc1 .Lmy_g2_passA1
	s_cmp_eq_u32 s0, 1
	s_cbranch_scc1 .Lmy_g2_passA2
	s_cmp_eq_u32 s0, 2
	s_cbranch_scc1 .Lmy_g2_passB
	s_cmp_eq_u32 s0, 3
	s_cbranch_scc1 .Lmy_g2_passC
	s_branch .Lmy_g2_done
.Lmy_g2_passA1:
	s_movk_i32 s11, 0x4c
	s_mov_b64 s[40:41], 0
	s_movk_i32 s17, 0xf8
	s_add_i32 s30, s1, -8
	s_cmp_lt_u32 s1, 8
	s_cselect_b32 s30, 0x7fff, s30
	v_readlane_b32 s3, v253, 19
	v_readlane_b32 s8, v253, 18
	s_mov_b32 s98, 0
	v_writelane_b32 v255, s98, 63
	v_writelane_b32 v255, s98, 62
	s_mov_b64 s[52:53], -1
	s_mov_b64 s[38:39], 0
	s_branch .LBB0_1189
.Lmy_g2_passA2:
	s_mov_b32 s11, 4
	s_mov_b64 s[40:41], 0x2600000
	s_mov_b32 s17, 8
	s_cmp_lt_u32 s1, 8
	s_cselect_b32 s30, s1, 0x7fff
	v_readlane_b32 s3, v253, 19
	v_readlane_b32 s8, v253, 18
	s_mov_b32 s98, 0x4c00
	v_writelane_b32 v255, s98, 63
	s_mov_b32 s98, 0
	v_writelane_b32 v255, s98, 62
	s_mov_b64 s[52:53], -1
	s_mov_b64 s[38:39], 0
	s_branch .LBB0_1189
.Lmy_g2_passB:
	s_mov_b32 s11, 1
	s_mov_b64 s[40:41], 0x4000000
	s_mov_b32 s17, 8
	s_mov_b32 s30, s1
	v_readlane_b32 s3, v253, 19
	v_readlane_b32 s8, v253, 18
	s_mov_b32 s98, 0x8000
	v_writelane_b32 v255, s98, 63
	s_mov_b32 s98, 0
	v_writelane_b32 v255, s98, 62
	s_mov_b64 s[52:53], -1
	s_mov_b64 s[38:39], 0
	s_branch .LBB0_1189
.Lmy_g2_passC:
	s_movk_i32 s11, 0x30
	s_mov_b64 s[40:41], 0x2800000
	s_movk_i32 s17, 0xf8
	s_sub_i32 s30, 0xff, s1
	s_cmp_lt_u32 s1, 8
	s_cselect_b32 s30, 0x7fff, s30
	s_movk_i32 s3, 0x800
	s_mov_b32 s8, 0
	s_mov_b32 s98, 0x5000
	v_writelane_b32 v255, s98, 63
	s_mov_b32 s98, 1
	v_writelane_b32 v255, s98, 62
	s_mov_b64 s[52:53], -1
	s_mov_b64 s[38:39], 0
	s_branch .LBB0_1189
